# FF-IN K-loop: LDS-DMA loads use SGPR base + 32-bit VGPR offset (16 fewer 64-bit VALU adds per iteration)
# baseline (speedup 1.0000x reference)
; #define PG8_STAGE(bufoff, gbase, voff) do { _Pragma("unroll") for (int _i = 0; _i < 2; ++_i) \
;         __builtin_amdgcn_global_load_lds((const unsigned*)((const char*)(gbase) + (voff)[_i]), (PG8_LAS unsigned*)(lds + (bufoff) + ldsw + _i * 8192), 16, 0, 0); } while (0)
; #define PG8_LDA(dst, b, h) do { _Pragma("unroll") for (int m = 0; m < 4; ++m) _Pragma("unroll") for (int k = 0; k < 2; ++k) dst[m][k] = *(const PG8_LAS bf16x8*)(lds + PG8_SA(b, h) + aoff + m * 2048 + k * 1024); } while (0)
; #define PG8_LDB(dst, b, h) do { _Pragma("unroll") for (int n = 0; n < 2; ++n) _Pragma("unroll") for (int k = 0; k < 2; ++k) dst[n][k] = *(const PG8_LAS bf16x8*)(lds + PG8_SB(b, h) + boff + n * 2048 + k * 1024); } while (0)
; #define PG8_MMA(ai, bj, At, Bt) do { __builtin_amdgcn_s_setprio(1); _Pragma("unroll") for (int m = 0; m < 4; ++m) _Pragma("unroll") for (int n = 0; n < 2; ++n) _Pragma("unroll") for (int k = 0; k < 2; ++k) \
;         acc[ai][bj][m][n] = __builtin_amdgcn_mfma_f32_16x16x32_bf16(Bt[n][k], At[m][k], acc[ai][bj][m][n], 0, 0, 0); __builtin_amdgcn_s_setprio(0); } while (0)
; #define PG8_WAIT_V(n) asm volatile("s_waitcnt vmcnt(" #n ")" ::: "memory")
; #define PG8_WAIT_L(n) asm volatile("s_waitcnt lgkmcnt(" #n ")" ::: "memory")
; #define PG8_BAR __builtin_amdgcn_s_barrier()
; #define PG8_SCHED __builtin_amdgcn_sched_barrier(0)
; template <class Epi, class Sched, bool ALIGN_EPI = false, bool SP2 = false>
; __device__ __forceinline__ void gemm_phase(PG8_LAS unsigned char* lds, const Gemm g, const Sched& S, const Epi& E) {
;     ...
;             PG8_LDB(B0, 0, 0); PG8_LDB(B1, 0, 1); PG8_SCHED; PG8_LDA(At, 0, 0); PG8_STAGE(PG8_SA(1, 1), a1 + hstep, voffA);
;             PG8_WAIT_V(8); PG8_WAIT_L(0); PG8_BAR; PG8_MMA(0, 0, At, B0); PG8_MMA(0, 1, At, B1); PG8_BAR; PG8_SCHED;
;     ...
; #pragma unroll
;         for (int a = 0; a < 2; ++a)
; #pragma unroll
;             for (int b = 0; b < 2; ++b)
; #pragma unroll
;                 for (int m = 0; m < 4; ++m)
; #pragma unroll
;                     for (int n = 0; n < 2; ++n) acc[a][b][m][n] = (f32x4){0.f, 0.f, 0.f, 0.f};
.Lffin_nopf:
	v_add_u32_e32 v118, s69, v229
	v_add_u32_e32 v134, s72, v229
	ds_read_b128 v[106:109], v118
	ds_read_b128 v[110:113], v118 offset:1024
	ds_read_b128 v[114:117], v118 offset:2048
	ds_read_b128 v[118:121], v118 offset:3072
	ds_read_b128 v[122:125], v134
	ds_read_b128 v[126:129], v134 offset:1024
	ds_read_b128 v[130:133], v134 offset:2048
	ds_read_b128 v[134:137], v134 offset:3072
	s_add_i32 m0, s53, 0xc000
	ds_read_b128 v[162:165], v230
	ds_read_b128 v[166:169], v230 offset:1024
	ds_read_b128 v[170:173], v230 offset:2048
	ds_read_b128 v[192:195], v230 offset:3072
	ds_read_b128 v[196:199], v230 offset:4096
	ds_read_b128 v[200:203], v230 offset:5120
	ds_read_b128 v[204:207], v230 offset:6144
	ds_read_b128 v[208:211], v230 offset:7168
	global_load_lds_dwordx4 v188, s[8:9]
	s_add_i32 m0, s53, 0xe000
	s_nop 0
	global_load_lds_dwordx4 v190, s[8:9]
	s_cmp_lg_u32 s68, -2
	s_cbranch_scc1 .Lffin_noz
	v_mov_b32_e32 v2, 0
	v_mov_b32_e32 v3, v2
	v_mov_b32_e32 v4, v2
	v_mov_b32_e32 v5, v2
	v_mov_b32_e32 v6, v2
	v_mov_b32_e32 v7, v2
	v_mov_b32_e32 v8, v2
	v_mov_b32_e32 v9, v2
	v_mov_b32_e32 v18, v2
	v_mov_b32_e32 v19, v2
	v_mov_b32_e32 v20, v2
	v_mov_b32_e32 v21, v2
	v_mov_b32_e32 v22, v2
	v_mov_b32_e32 v23, v2
	v_mov_b32_e32 v24, v2
	v_mov_b32_e32 v25, v2
	v_mov_b32_e32 v34, v2
	v_mov_b32_e32 v35, v2
	v_mov_b32_e32 v36, v2
	v_mov_b32_e32 v37, v2
	v_mov_b32_e32 v38, v2
	v_mov_b32_e32 v39, v2
	v_mov_b32_e32 v40, v2
	v_mov_b32_e32 v41, v2
	v_mov_b32_e32 v50, v2
	v_mov_b32_e32 v51, v2
	v_mov_b32_e32 v52, v2
	v_mov_b32_e32 v53, v2
	v_mov_b32_e32 v54, v2
	v_mov_b32_e32 v55, v2
	v_mov_b32_e32 v56, v2
	v_mov_b32_e32 v57, v2
	v_mov_b32_e32 v10, v2
	v_mov_b32_e32 v11, v2
	v_mov_b32_e32 v12, v2
	v_mov_b32_e32 v13, v2
	v_mov_b32_e32 v14, v2
	v_mov_b32_e32 v15, v2
	v_mov_b32_e32 v16, v2
	v_mov_b32_e32 v17, v2
	v_mov_b32_e32 v26, v2
	v_mov_b32_e32 v27, v2
	v_mov_b32_e32 v28, v2
	v_mov_b32_e32 v29, v2
	v_mov_b32_e32 v30, v2
	v_mov_b32_e32 v31, v2
	v_mov_b32_e32 v32, v2
	v_mov_b32_e32 v33, v2
	v_mov_b32_e32 v42, v2
	v_mov_b32_e32 v43, v2
	v_mov_b32_e32 v44, v2
	v_mov_b32_e32 v45, v2
	v_mov_b32_e32 v46, v2
	v_mov_b32_e32 v47, v2
	v_mov_b32_e32 v48, v2
	v_mov_b32_e32 v49, v2
	v_mov_b32_e32 v58, v2
	v_mov_b32_e32 v59, v2
	v_mov_b32_e32 v60, v2
	v_mov_b32_e32 v61, v2
	v_mov_b32_e32 v62, v2
	v_mov_b32_e32 v63, v2
	v_mov_b32_e32 v64, v2
	v_mov_b32_e32 v65, v2
	v_mov_b32_e32 v66, v2
	v_mov_b32_e32 v67, v2
	v_mov_b32_e32 v68, v2
	v_mov_b32_e32 v69, v2
	v_mov_b32_e32 v70, v2
	v_mov_b32_e32 v71, v2
	v_mov_b32_e32 v72, v2
	v_mov_b32_e32 v73, v2
	v_mov_b32_e32 v82, v2
	v_mov_b32_e32 v83, v2
	v_mov_b32_e32 v84, v2
	v_mov_b32_e32 v85, v2
	v_mov_b32_e32 v86, v2
	v_mov_b32_e32 v87, v2
	v_mov_b32_e32 v88, v2
	v_mov_b32_e32 v89, v2
	v_mov_b32_e32 v98, v2
	v_mov_b32_e32 v99, v2
	v_mov_b32_e32 v100, v2
	v_mov_b32_e32 v101, v2
	v_mov_b32_e32 v102, v2
	v_mov_b32_e32 v103, v2
	v_mov_b32_e32 v104, v2
	v_mov_b32_e32 v105, v2
	v_mov_b32_e32 v146, v2
	v_mov_b32_e32 v147, v2
	v_mov_b32_e32 v148, v2
	v_mov_b32_e32 v149, v2
	v_mov_b32_e32 v150, v2
	v_mov_b32_e32 v151, v2
	v_mov_b32_e32 v152, v2
	v_mov_b32_e32 v153, v2
	v_mov_b32_e32 v74, v2
	v_mov_b32_e32 v75, v2
	v_mov_b32_e32 v76, v2
	v_mov_b32_e32 v77, v2
	v_mov_b32_e32 v78, v2
	v_mov_b32_e32 v79, v2
	v_mov_b32_e32 v80, v2
	v_mov_b32_e32 v81, v2
	v_mov_b32_e32 v90, v2
	v_mov_b32_e32 v91, v2
	v_mov_b32_e32 v92, v2
	v_mov_b32_e32 v93, v2
	v_mov_b32_e32 v94, v2
	v_mov_b32_e32 v95, v2
	v_mov_b32_e32 v96, v2
	v_mov_b32_e32 v97, v2
	v_mov_b32_e32 v138, v2
	v_mov_b32_e32 v139, v2
	v_mov_b32_e32 v140, v2
	v_mov_b32_e32 v141, v2
	v_mov_b32_e32 v142, v2
	v_mov_b32_e32 v143, v2
	v_mov_b32_e32 v144, v2
	v_mov_b32_e32 v145, v2
	v_mov_b32_e32 v154, v2
	v_mov_b32_e32 v155, v2
	v_mov_b32_e32 v156, v2
	v_mov_b32_e32 v157, v2
	v_mov_b32_e32 v158, v2
	v_mov_b32_e32 v159, v2
	v_mov_b32_e32 v160, v2
	v_mov_b32_e32 v161, v2
; #define PG8_STAGE(bufoff, gbase, voff) do { _Pragma("unroll") for (int _i = 0; _i < 2; ++_i) \
;         __builtin_amdgcn_global_load_lds((const unsigned*)((const char*)(gbase) + (voff)[_i]), (PG8_LAS unsigned*)(lds + (bufoff) + ldsw + _i * 8192), 16, 0, 0); } while (0)
; #define PG8_LDA(dst, b, h) do { _Pragma("unroll") for (int m = 0; m < 4; ++m) _Pragma("unroll") for (int k = 0; k < 2; ++k) dst[m][k] = *(const PG8_LAS bf16x8*)(lds + PG8_SA(b, h) + aoff + m * 2048 + k * 1024); } while (0)
; #define PG8_MMA(ai, bj, At, Bt) do { __builtin_amdgcn_s_setprio(1); _Pragma("unroll") for (int m = 0; m < 4; ++m) _Pragma("unroll") for (int n = 0; n < 2; ++n) _Pragma("unroll") for (int k = 0; k < 2; ++k) \
;         acc[ai][bj][m][n] = __builtin_amdgcn_mfma_f32_16x16x32_bf16(Bt[n][k], At[m][k], acc[ai][bj][m][n], 0, 0, 0); __builtin_amdgcn_s_setprio(0); } while (0)
; #define PG8_WAIT_V(n) asm volatile("s_waitcnt vmcnt(" #n ")" ::: "memory")
; #define PG8_WAIT_L(n) asm volatile("s_waitcnt lgkmcnt(" #n ")" ::: "memory")
; #define PG8_BAR __builtin_amdgcn_s_barrier()
; #define PG8_SCHED __builtin_amdgcn_sched_barrier(0)
; template <class Epi, class Sched, bool ALIGN_EPI = false, bool SP2 = false>
; __device__ __forceinline__ void gemm_phase(PG8_LAS unsigned char* lds, const Gemm g, const Sched& S, const Epi& E) {
;     ...
;             PG8_WAIT_V(8); PG8_WAIT_L(0); PG8_BAR; PG8_MMA(0, 0, At, B0); PG8_MMA(0, 1, At, B1); PG8_BAR; PG8_SCHED;
;             PG8_LDA(At, 0, 1); PG8_STAGE(PG8_SB(0, 0), b2, voffB); PG8_STAGE(PG8_SB(0, 1), b2 + hstep, voffB); PG8_STAGE(PG8_SA(0, 0), a2, voffA);
;             PG8_WAIT_V(8); PG8_WAIT_L(0); PG8_BAR; PG8_MMA(1, 0, At, B0); PG8_MMA(1, 1, At, B1); PG8_BAR; PG8_SCHED;
.Lffin_noz:
	s_waitcnt vmcnt(8)
	s_waitcnt lgkmcnt(0)
	s_barrier
	s_setprio 1
	s_waitcnt lgkmcnt(0)
	v_mfma_f32_16x16x32_bf16 v[158:161], v[106:109], v[162:165], v[158:161]
	v_mfma_f32_16x16x32_bf16 v[154:157], v[114:117], v[162:165], v[154:157]
	v_mfma_f32_16x16x32_bf16 v[142:145], v[106:109], v[170:173], v[142:145]
	v_mfma_f32_16x16x32_bf16 v[138:141], v[114:117], v[170:173], v[138:141]
	v_mfma_f32_16x16x32_bf16 v[94:97], v[106:109], v[196:199], v[94:97]
	v_mfma_f32_16x16x32_bf16 v[90:93], v[114:117], v[196:199], v[90:93]
	v_mfma_f32_16x16x32_bf16 v[78:81], v[106:109], v[204:207], v[78:81]
	v_mfma_f32_16x16x32_bf16 v[74:77], v[114:117], v[204:207], v[74:77]
	v_mfma_f32_16x16x32_bf16 v[158:161], v[110:113], v[166:169], v[158:161]
	v_mfma_f32_16x16x32_bf16 v[154:157], v[118:121], v[166:169], v[154:157]
	v_mfma_f32_16x16x32_bf16 v[142:145], v[110:113], v[192:195], v[142:145]
	v_mfma_f32_16x16x32_bf16 v[138:141], v[118:121], v[192:195], v[138:141]
	v_mfma_f32_16x16x32_bf16 v[94:97], v[110:113], v[200:203], v[94:97]
	v_mfma_f32_16x16x32_bf16 v[90:93], v[118:121], v[200:203], v[90:93]
	v_mfma_f32_16x16x32_bf16 v[78:81], v[110:113], v[208:211], v[78:81]
	v_mfma_f32_16x16x32_bf16 v[74:77], v[118:121], v[208:211], v[74:77]
	s_setprio 0
	s_setprio 1
	v_mfma_f32_16x16x32_bf16 v[150:153], v[122:125], v[162:165], v[150:153]
	v_mfma_f32_16x16x32_bf16 v[146:149], v[130:133], v[162:165], v[146:149]
	v_mfma_f32_16x16x32_bf16 v[102:105], v[122:125], v[170:173], v[102:105]
	v_mfma_f32_16x16x32_bf16 v[98:101], v[130:133], v[170:173], v[98:101]
	v_mfma_f32_16x16x32_bf16 v[86:89], v[122:125], v[196:199], v[86:89]
	v_mfma_f32_16x16x32_bf16 v[82:85], v[130:133], v[196:199], v[82:85]
	v_mfma_f32_16x16x32_bf16 v[70:73], v[122:125], v[204:207], v[70:73]
	v_mfma_f32_16x16x32_bf16 v[66:69], v[130:133], v[204:207], v[66:69]
	v_mfma_f32_16x16x32_bf16 v[150:153], v[126:129], v[166:169], v[150:153]
	v_mfma_f32_16x16x32_bf16 v[146:149], v[134:137], v[166:169], v[146:149]
	v_mfma_f32_16x16x32_bf16 v[102:105], v[126:129], v[192:195], v[102:105]
	v_mfma_f32_16x16x32_bf16 v[98:101], v[134:137], v[192:195], v[98:101]
	v_mfma_f32_16x16x32_bf16 v[86:89], v[126:129], v[200:203], v[86:89]
	v_mfma_f32_16x16x32_bf16 v[82:85], v[134:137], v[200:203], v[82:85]
	v_mfma_f32_16x16x32_bf16 v[70:73], v[126:129], v[208:211], v[70:73]
	v_mfma_f32_16x16x32_bf16 v[66:69], v[134:137], v[208:211], v[66:69]
	s_setprio 0
	s_barrier
	s_add_i32 s69, s69, s52
	s_mov_b32 m0, s69
	ds_read_b128 v[162:165], v230 offset:16384
	ds_read_b128 v[166:169], v230 offset:17408
	ds_read_b128 v[170:173], v230 offset:18432
	ds_read_b128 v[192:195], v230 offset:19456
	ds_read_b128 v[196:199], v230 offset:20480
	ds_read_b128 v[200:203], v230 offset:21504
	ds_read_b128 v[204:207], v230 offset:22528
	ds_read_b128 v[208:211], v230 offset:23552
	global_load_lds_dwordx4 v184, s[44:45]
	s_add_i32 m0, s69, 0x2000
	s_add_u32 s70, s44, 0x40000
	s_addc_u32 s71, s45, 0
	s_add_i32 s69, s72, s52
	global_load_lds_dwordx4 v180, s[44:45]
	s_mov_b32 m0, s69
	s_nop 0
	global_load_lds_dwordx4 v184, s[70:71]
	s_add_i32 m0, s69, 0x2000
	s_nop 0
	global_load_lds_dwordx4 v180, s[70:71]
	s_mov_b32 m0, s53
	s_nop 0
	global_load_lds_dwordx4 v186, s[46:47]
	s_mov_b32 m0, s54
	s_nop 0
	global_load_lds_dwordx4 v182, s[46:47]
	s_cmp_lg_u32 s68, -2
	s_cbranch_scc1 .Lffin_w8
	s_cmp_lt_u32 s57, 2
	s_cbranch_scc1 .Lffin_w8
	s_waitcnt vmcnt(16)
	s_branch .Lffin_wd

; #define PG8_STAGE(bufoff, gbase, voff) do { _Pragma("unroll") for (int _i = 0; _i < 2; ++_i) \
;         __builtin_amdgcn_global_load_lds((const unsigned*)((const char*)(gbase) + (voff)[_i]), (PG8_LAS unsigned*)(lds + (bufoff) + ldsw + _i * 8192), 16, 0, 0); } while (0)
; #define PG8_LDA(dst, b, h) do { _Pragma("unroll") for (int m = 0; m < 4; ++m) _Pragma("unroll") for (int k = 0; k < 2; ++k) dst[m][k] = *(const PG8_LAS bf16x8*)(lds + PG8_SA(b, h) + aoff + m * 2048 + k * 1024); } while (0)
; #define PG8_LDB(dst, b, h) do { _Pragma("unroll") for (int n = 0; n < 2; ++n) _Pragma("unroll") for (int k = 0; k < 2; ++k) dst[n][k] = *(const PG8_LAS bf16x8*)(lds + PG8_SB(b, h) + boff + n * 2048 + k * 1024); } while (0)
; #define PG8_MMA(ai, bj, At, Bt) do { __builtin_amdgcn_s_setprio(1); _Pragma("unroll") for (int m = 0; m < 4; ++m) _Pragma("unroll") for (int n = 0; n < 2; ++n) _Pragma("unroll") for (int k = 0; k < 2; ++k) \
;         acc[ai][bj][m][n] = __builtin_amdgcn_mfma_f32_16x16x32_bf16(Bt[n][k], At[m][k], acc[ai][bj][m][n], 0, 0, 0); __builtin_amdgcn_s_setprio(0); } while (0)
; #define PG8_WAIT_V(n) asm volatile("s_waitcnt vmcnt(" #n ")" ::: "memory")
; #define PG8_WAIT_L(n) asm volatile("s_waitcnt lgkmcnt(" #n ")" ::: "memory")
; #define PG8_BAR __builtin_amdgcn_s_barrier()
; #define PG8_SCHED __builtin_amdgcn_sched_barrier(0)
; template <class Epi, class Sched, bool ALIGN_EPI = false, bool SP2 = false>
; __device__ __forceinline__ void gemm_phase(PG8_LAS unsigned char* lds, const Gemm g, const Sched& S, const Epi& E) {
;     ...
;             PG8_WAIT_V(8); PG8_WAIT_L(0); PG8_BAR; PG8_MMA(1, 0, At, B0); PG8_MMA(1, 1, At, B1); PG8_BAR; PG8_SCHED;
;             PG8_LDB(B0, 1, 0); PG8_LDB(B1, 1, 1); PG8_SCHED; PG8_LDA(At, 1, 0); PG8_STAGE(PG8_SA(0, 1), a2 + hstep, voffA);
;             PG8_WAIT_V(8); PG8_WAIT_L(0); PG8_BAR; PG8_MMA(0, 0, At, B0); PG8_MMA(0, 1, At, B1); PG8_BAR; PG8_SCHED;
.Lffin_wd:
	s_waitcnt lgkmcnt(0)
	s_barrier
	s_setprio 1
	s_waitcnt lgkmcnt(0)
	v_mfma_f32_16x16x32_bf16 v[62:65], v[106:109], v[162:165], v[62:65]
	v_mfma_f32_16x16x32_bf16 v[58:61], v[114:117], v[162:165], v[58:61]
	v_mfma_f32_16x16x32_bf16 v[46:49], v[106:109], v[170:173], v[46:49]
	v_mfma_f32_16x16x32_bf16 v[42:45], v[114:117], v[170:173], v[42:45]
	v_mfma_f32_16x16x32_bf16 v[30:33], v[106:109], v[196:199], v[30:33]
	v_mfma_f32_16x16x32_bf16 v[26:29], v[114:117], v[196:199], v[26:29]
	v_mfma_f32_16x16x32_bf16 v[14:17], v[106:109], v[204:207], v[14:17]
	v_mfma_f32_16x16x32_bf16 v[10:13], v[114:117], v[204:207], v[10:13]
	v_mfma_f32_16x16x32_bf16 v[62:65], v[110:113], v[166:169], v[62:65]
	v_mfma_f32_16x16x32_bf16 v[58:61], v[118:121], v[166:169], v[58:61]
	v_mfma_f32_16x16x32_bf16 v[46:49], v[110:113], v[192:195], v[46:49]
	v_mfma_f32_16x16x32_bf16 v[42:45], v[118:121], v[192:195], v[42:45]
	v_mfma_f32_16x16x32_bf16 v[30:33], v[110:113], v[200:203], v[30:33]
	v_mfma_f32_16x16x32_bf16 v[26:29], v[118:121], v[200:203], v[26:29]
	v_mfma_f32_16x16x32_bf16 v[14:17], v[110:113], v[208:211], v[14:17]
	v_mfma_f32_16x16x32_bf16 v[10:13], v[118:121], v[208:211], v[10:13]
	s_setprio 0
	s_setprio 1
	v_mfma_f32_16x16x32_bf16 v[54:57], v[122:125], v[162:165], v[54:57]
	v_mfma_f32_16x16x32_bf16 v[50:53], v[130:133], v[162:165], v[50:53]
	v_mfma_f32_16x16x32_bf16 v[38:41], v[122:125], v[170:173], v[38:41]
	v_mfma_f32_16x16x32_bf16 v[34:37], v[130:133], v[170:173], v[34:37]
	v_mfma_f32_16x16x32_bf16 v[22:25], v[122:125], v[196:199], v[22:25]
	v_mfma_f32_16x16x32_bf16 v[18:21], v[130:133], v[196:199], v[18:21]
	v_mfma_f32_16x16x32_bf16 v[6:9], v[122:125], v[204:207], v[6:9]
	v_mfma_f32_16x16x32_bf16 v[2:5], v[130:133], v[204:207], v[2:5]
	v_mfma_f32_16x16x32_bf16 v[54:57], v[126:129], v[166:169], v[54:57]
	v_mfma_f32_16x16x32_bf16 v[50:53], v[134:137], v[166:169], v[50:53]
	v_mfma_f32_16x16x32_bf16 v[38:41], v[126:129], v[192:195], v[38:41]
	v_mfma_f32_16x16x32_bf16 v[34:37], v[134:137], v[192:195], v[34:37]
	v_mfma_f32_16x16x32_bf16 v[22:25], v[126:129], v[200:203], v[22:25]
	v_mfma_f32_16x16x32_bf16 v[18:21], v[134:137], v[200:203], v[18:21]
	v_mfma_f32_16x16x32_bf16 v[6:9], v[126:129], v[208:211], v[6:9]
	v_mfma_f32_16x16x32_bf16 v[2:5], v[134:137], v[208:211], v[2:5]
	s_setprio 0
	s_barrier
	s_add_i32 s69, 0, 0x18000
	s_add_i32 s70, 0, 0x1c000
	v_add_u32_e32 v118, s69, v229
	v_add_u32_e32 v134, s70, v229
	ds_read_b128 v[106:109], v118
	ds_read_b128 v[110:113], v118 offset:1024
	ds_read_b128 v[114:117], v118 offset:2048
	ds_read_b128 v[118:121], v118 offset:3072
	ds_read_b128 v[122:125], v134
	ds_read_b128 v[126:129], v134 offset:1024
	ds_read_b128 v[130:133], v134 offset:2048
	ds_read_b128 v[134:137], v134 offset:3072
	s_add_u32 s46, s46, 0x40000
	s_addc_u32 s47, s47, 0
	s_mov_b32 m0, s55
	ds_read_b128 v[162:165], v230 offset:32768
	ds_read_b128 v[166:169], v230 offset:33792
	ds_read_b128 v[170:173], v230 offset:34816
	ds_read_b128 v[192:195], v230 offset:35840
	ds_read_b128 v[196:199], v230 offset:36864
	ds_read_b128 v[200:203], v230 offset:37888
	ds_read_b128 v[204:207], v230 offset:38912
	ds_read_b128 v[208:211], v230 offset:39936
	global_load_lds_dwordx4 v186, s[46:47]
	s_mov_b32 m0, s56
	s_nop 0
	global_load_lds_dwordx4 v182, s[46:47]
	s_waitcnt vmcnt(8)
	s_waitcnt lgkmcnt(0)
	s_barrier
	s_setprio 1
	s_waitcnt lgkmcnt(0)
	v_mfma_f32_16x16x32_bf16 v[158:161], v[106:109], v[162:165], v[158:161]
	v_mfma_f32_16x16x32_bf16 v[154:157], v[114:117], v[162:165], v[154:157]
	v_mfma_f32_16x16x32_bf16 v[142:145], v[106:109], v[170:173], v[142:145]
	v_mfma_f32_16x16x32_bf16 v[138:141], v[114:117], v[170:173], v[138:141]
	v_mfma_f32_16x16x32_bf16 v[94:97], v[106:109], v[196:199], v[94:97]
	v_mfma_f32_16x16x32_bf16 v[90:93], v[114:117], v[196:199], v[90:93]
	v_mfma_f32_16x16x32_bf16 v[78:81], v[106:109], v[204:207], v[78:81]
	v_mfma_f32_16x16x32_bf16 v[74:77], v[114:117], v[204:207], v[74:77]
	v_mfma_f32_16x16x32_bf16 v[158:161], v[110:113], v[166:169], v[158:161]
	v_mfma_f32_16x16x32_bf16 v[154:157], v[118:121], v[166:169], v[154:157]
	v_mfma_f32_16x16x32_bf16 v[142:145], v[110:113], v[192:195], v[142:145]
	v_mfma_f32_16x16x32_bf16 v[138:141], v[118:121], v[192:195], v[138:141]
	v_mfma_f32_16x16x32_bf16 v[94:97], v[110:113], v[200:203], v[94:97]
	v_mfma_f32_16x16x32_bf16 v[90:93], v[118:121], v[200:203], v[90:93]
	v_mfma_f32_16x16x32_bf16 v[78:81], v[110:113], v[208:211], v[78:81]
	v_mfma_f32_16x16x32_bf16 v[74:77], v[118:121], v[208:211], v[74:77]
	s_setprio 0
	s_setprio 1
	v_mfma_f32_16x16x32_bf16 v[150:153], v[122:125], v[162:165], v[150:153]
	v_mfma_f32_16x16x32_bf16 v[146:149], v[130:133], v[162:165], v[146:149]
	v_mfma_f32_16x16x32_bf16 v[102:105], v[122:125], v[170:173], v[102:105]
	v_mfma_f32_16x16x32_bf16 v[98:101], v[130:133], v[170:173], v[98:101]
	v_mfma_f32_16x16x32_bf16 v[86:89], v[122:125], v[196:199], v[86:89]
	v_mfma_f32_16x16x32_bf16 v[82:85], v[130:133], v[196:199], v[82:85]
	v_mfma_f32_16x16x32_bf16 v[70:73], v[122:125], v[204:207], v[70:73]
	v_mfma_f32_16x16x32_bf16 v[66:69], v[130:133], v[204:207], v[66:69]
	v_mfma_f32_16x16x32_bf16 v[150:153], v[126:129], v[166:169], v[150:153]
	v_mfma_f32_16x16x32_bf16 v[146:149], v[134:137], v[166:169], v[146:149]
	v_mfma_f32_16x16x32_bf16 v[102:105], v[126:129], v[192:195], v[102:105]
	v_mfma_f32_16x16x32_bf16 v[98:101], v[134:137], v[192:195], v[98:101]
	v_mfma_f32_16x16x32_bf16 v[86:89], v[126:129], v[200:203], v[86:89]
	v_mfma_f32_16x16x32_bf16 v[82:85], v[134:137], v[200:203], v[82:85]
	v_mfma_f32_16x16x32_bf16 v[70:73], v[126:129], v[208:211], v[70:73]
	v_mfma_f32_16x16x32_bf16 v[66:69], v[134:137], v[208:211], v[66:69]
	s_setprio 0
	s_barrier
; #define PG8_STAGE(bufoff, gbase, voff) do { _Pragma("unroll") for (int _i = 0; _i < 2; ++_i) \
;         __builtin_amdgcn_global_load_lds((const unsigned*)((const char*)(gbase) + (voff)[_i]), (PG8_LAS unsigned*)(lds + (bufoff) + ldsw + _i * 8192), 16, 0, 0); } while (0)
; #define PG8_LDA(dst, b, h) do { _Pragma("unroll") for (int m = 0; m < 4; ++m) _Pragma("unroll") for (int k = 0; k < 2; ++k) dst[m][k] = *(const PG8_LAS bf16x8*)(lds + PG8_SA(b, h) + aoff + m * 2048 + k * 1024); } while (0)
; #define PG8_MMA(ai, bj, At, Bt) do { __builtin_amdgcn_s_setprio(1); _Pragma("unroll") for (int m = 0; m < 4; ++m) _Pragma("unroll") for (int n = 0; n < 2; ++n) _Pragma("unroll") for (int k = 0; k < 2; ++k) \
;         acc[ai][bj][m][n] = __builtin_amdgcn_mfma_f32_16x16x32_bf16(Bt[n][k], At[m][k], acc[ai][bj][m][n], 0, 0, 0); __builtin_amdgcn_s_setprio(0); } while (0)
; #define PG8_WAIT_V(n) asm volatile("s_waitcnt vmcnt(" #n ")" ::: "memory")
; #define PG8_WAIT_L(n) asm volatile("s_waitcnt lgkmcnt(" #n ")" ::: "memory")
; #define PG8_BAR __builtin_amdgcn_s_barrier()
; #define PG8_SCHED __builtin_amdgcn_sched_barrier(0)
; template <class Epi, class Sched, bool ALIGN_EPI = false, bool SP2 = false>
; __device__ __forceinline__ void gemm_phase(PG8_LAS unsigned char* lds, const Gemm g, const Sched& S, const Epi& E) {
;     ...
;         for (int t = 0; t < nt; t += 2) {
;             const bool last = (t == nt - 2);
;     ...
;             PG8_LDA(At, 1, 1); PG8_STAGE(PG8_SB(1, 0), b3, voffB); PG8_STAGE(PG8_SB(1, 1), b3 + hstep, voffB); PG8_STAGE(PG8_SA(1, 0), a3, voffA);
;             PG8_WAIT_V(8); PG8_WAIT_L(0); PG8_BAR; PG8_MMA(1, 0, At, B0); PG8_MMA(1, 1, At, B1); PG8_BAR; PG8_SCHED;
	s_add_u32 s100, s46, 0xfffc0080
	s_addc_u32 s101, s47, -1
	s_add_u32 s98, s44, 0x80
	s_addc_u32 s99, s45, 0
	s_add_i32 s46, s69, s52
	s_mov_b32 m0, s46
	ds_read_b128 v[162:165], v230 offset:49152
	ds_read_b128 v[166:169], v230 offset:50176
	ds_read_b128 v[170:173], v230 offset:51200
	ds_read_b128 v[192:195], v230 offset:52224
	ds_read_b128 v[196:199], v230 offset:53248
	ds_read_b128 v[200:203], v230 offset:54272
	ds_read_b128 v[204:207], v230 offset:55296
	ds_read_b128 v[208:211], v230 offset:56320
	global_load_lds_dwordx4 v184, s[98:99]
	s_add_i32 m0, s46, 0x2000
	s_add_u32 s44, s44, 0x40080
	s_addc_u32 s45, s45, 0
	s_add_i32 s46, s70, s52
	global_load_lds_dwordx4 v180, s[98:99]
	s_mov_b32 m0, s46
	s_nop 0
	global_load_lds_dwordx4 v184, s[44:45]
	s_add_i32 m0, s46, 0x2000
	s_nop 0
	global_load_lds_dwordx4 v180, s[44:45]
	s_mov_b32 m0, s60
	s_nop 0
	global_load_lds_dwordx4 v186, s[100:101]
	s_mov_b32 m0, s61
	s_nop 0
	global_load_lds_dwordx4 v182, s[100:101]
	s_waitcnt vmcnt(8)
	s_waitcnt lgkmcnt(0)
	s_barrier
	s_setprio 1
	s_waitcnt lgkmcnt(0)
	v_mfma_f32_16x16x32_bf16 v[62:65], v[106:109], v[162:165], v[62:65]
	v_mfma_f32_16x16x32_bf16 v[58:61], v[114:117], v[162:165], v[58:61]
	v_mfma_f32_16x16x32_bf16 v[46:49], v[106:109], v[170:173], v[46:49]
	v_mfma_f32_16x16x32_bf16 v[42:45], v[114:117], v[170:173], v[42:45]
	v_mfma_f32_16x16x32_bf16 v[30:33], v[106:109], v[196:199], v[30:33]
	v_mfma_f32_16x16x32_bf16 v[26:29], v[114:117], v[196:199], v[26:29]
	v_mfma_f32_16x16x32_bf16 v[14:17], v[106:109], v[204:207], v[14:17]
	v_mfma_f32_16x16x32_bf16 v[10:13], v[114:117], v[204:207], v[10:13]
	v_mfma_f32_16x16x32_bf16 v[62:65], v[110:113], v[166:169], v[62:65]
	v_mfma_f32_16x16x32_bf16 v[58:61], v[118:121], v[166:169], v[58:61]
	v_mfma_f32_16x16x32_bf16 v[46:49], v[110:113], v[192:195], v[46:49]
	v_mfma_f32_16x16x32_bf16 v[42:45], v[118:121], v[192:195], v[42:45]
	v_mfma_f32_16x16x32_bf16 v[30:33], v[110:113], v[200:203], v[30:33]
	v_mfma_f32_16x16x32_bf16 v[26:29], v[118:121], v[200:203], v[26:29]
	v_mfma_f32_16x16x32_bf16 v[14:17], v[110:113], v[208:211], v[14:17]
	v_mfma_f32_16x16x32_bf16 v[10:13], v[118:121], v[208:211], v[10:13]
	s_setprio 0
	s_setprio 1
	v_mfma_f32_16x16x32_bf16 v[54:57], v[122:125], v[162:165], v[54:57]
	v_mfma_f32_16x16x32_bf16 v[50:53], v[130:133], v[162:165], v[50:53]
	v_mfma_f32_16x16x32_bf16 v[38:41], v[122:125], v[170:173], v[38:41]
	v_mfma_f32_16x16x32_bf16 v[34:37], v[130:133], v[170:173], v[34:37]
	v_mfma_f32_16x16x32_bf16 v[22:25], v[122:125], v[196:199], v[22:25]
	v_mfma_f32_16x16x32_bf16 v[18:21], v[130:133], v[196:199], v[18:21]
	v_mfma_f32_16x16x32_bf16 v[6:9], v[122:125], v[204:207], v[6:9]
	v_mfma_f32_16x16x32_bf16 v[2:5], v[130:133], v[204:207], v[2:5]
	v_mfma_f32_16x16x32_bf16 v[54:57], v[126:129], v[166:169], v[54:57]
	v_mfma_f32_16x16x32_bf16 v[50:53], v[134:137], v[166:169], v[50:53]
	v_mfma_f32_16x16x32_bf16 v[38:41], v[126:129], v[192:195], v[38:41]
	v_mfma_f32_16x16x32_bf16 v[34:37], v[134:137], v[192:195], v[34:37]
	v_mfma_f32_16x16x32_bf16 v[22:25], v[126:129], v[200:203], v[22:25]
	v_mfma_f32_16x16x32_bf16 v[18:21], v[134:137], v[200:203], v[18:21]
	v_mfma_f32_16x16x32_bf16 v[6:9], v[126:129], v[208:211], v[6:9]
	v_mfma_f32_16x16x32_bf16 v[2:5], v[134:137], v[208:211], v[2:5]
	s_setprio 0
	s_barrier
	s_add_i32 s68, s68, 2
	s_add_u32 s8, s8, 0x100
	s_addc_u32 s9, s9, 0
	s_add_u32 s66, s66, 0x100
	s_addc_u32 s67, s67, 0
	s_cmp_gt_u32 s68, 13
	s_cbranch_scc0 .LBB0_1247
	s_and_b64 vcc, exec, s[24:25]
	s_cbranch_vccz .LBB0_1250
	s_barrier
